# seams out-proj->FF1 and FF1->FF2 synchronize only the 4 workgroups that share row panels (rank&7 groups, own L2 counters) instead of all 32 of the XCD
# baseline (speedup 1.0000x reference)
; __device__ __forceinline__ int lane_id() { int l; asm volatile("v_mbcnt_lo_u32_b32 %0, -1, 0\n\tv_mbcnt_hi_u32_b32 %0, -1, %0" : "=v"(l)); return l; }
; #define LAS __attribute__((address_space(3)))
; __device__ __forceinline__ unsigned xb_ld(unsigned* p)              { return __hip_atomic_load(p, __ATOMIC_RELAXED, __HIP_MEMORY_SCOPE_AGENT); }
; __device__ __forceinline__ unsigned xb_add(unsigned* p, unsigned v) { return __hip_atomic_fetch_add(p, v, __ATOMIC_RELAXED, __HIP_MEMORY_SCOPE_AGENT); }
; __device__ __forceinline__ unsigned xb_xcc_id() { return (unsigned)__builtin_amdgcn_s_getreg((3 << 11) | 20) & 0xFu; }
; __device__ __forceinline__ void placement_init(unsigned* bar, volatile LAS unsigned* st  , int wid0) {
;     if (wid0 == 0 && lane_id() == 0) {
;         const unsigned x = xb_xcc_id(), G = gridDim.x;
;         const unsigned rank = xb_add(&bar[XB_XCNT(x)], 1u);
;         unsigned c[16], sum, sp = 0u;
;         for (;;) { sum = 0u;
; #pragma unroll
;             for (unsigned j = 0; j < 16; ++j) { c[j] = xb_ld(&bar[XB_XCNT(j)]); sum += c[j]; }
;             if (sum == G) break;
;             __builtin_amdgcn_s_sleep(1);
;             if ((++sp & 255u) == 0u) { if (xb_ld(&bar[XB_TMO])) break; if (sp > XB_SPIN_CAP) { atomicAdd(&bar[XB_TMO], 1u); break; } } }
;         unsigned nx = 0u, jx = 0u, mine = 1u; bool even = true;
; #pragma unroll
;         for (unsigned j = 0; j < 16; ++j) { if (c[j] > 0u) { if (j < x) ++jx; ++nx; } if (j == x) mine = c[j] > 0u ? c[j] : 1u; }
; #pragma unroll
;         for (unsigned j = 0; j < 16; ++j) if (c[j] > 0u && c[j] != mine) even = false;
;         if (nx == 0u) nx = 1u;
;         st[0] = mine; st[1] = nx;
;         const bool local = even && (mine % 8u == 0u) && (16u % nx == 0u) && sum == G;
;         st[2] = local ? jx : 0u; st[3] = local ? rank : blockIdx.x; st[4] = local ? mine : G; st[5] = local ? nx : 1u; st[6] = 0u; st[7] = local ? 1u : 0u;
;         if (local && rank == 0u) { __hip_atomic_store(&bar[XB_LCNT2(x)], 0u, __ATOMIC_RELAXED, __HIP_MEMORY_SCOPE_WORKGROUP); asm volatile("s_waitcnt vmcnt(0)" ::: "memory"); }
;     }
;     __syncthreads();
; }
.LBB13_21:
	s_cmp_lg_u32 s3, 0
	s_cselect_b64 s[24:25], -1, 0
	s_and_b64 s[24:25], s[24:25], s[26:27]
	s_cmp_gt_u32 s3, 1
	v_cndmask_b32_e64 v2, 0, 1, s[24:25]
	s_cselect_b64 s[24:25], -1, 0
	s_and_b64 s[16:17], s[16:17], s[24:25]
	s_cmp_gt_u32 s3, 2
	v_cndmask_b32_e64 v3, 0, 1, s[16:17]
	s_cselect_b64 s[16:17], -1, 0
	s_and_b64 s[16:17], s[28:29], s[16:17]
	s_cmp_gt_u32 s3, 3
	v_cndmask_b32_e64 v4, 0, 1, s[16:17]
	s_cselect_b64 s[16:17], -1, 0
	s_and_b64 s[4:5], s[4:5], s[16:17]
	s_cmp_gt_u32 s3, 4
	v_cndmask_b32_e64 v5, 0, 1, s[4:5]
	s_cselect_b64 s[4:5], -1, 0
	s_and_b64 s[4:5], s[30:31], s[4:5]
	s_cmp_gt_u32 s3, 5
	v_cndmask_b32_e64 v6, 0, 1, s[4:5]
	s_cselect_b64 s[4:5], -1, 0
	s_and_b64 s[4:5], s[6:7], s[4:5]
	s_cmp_gt_u32 s3, 6
	v_cndmask_b32_e64 v7, 0, 1, s[4:5]
	s_cselect_b64 s[4:5], -1, 0
	s_and_b64 s[4:5], s[34:35], s[4:5]
	s_cmp_gt_u32 s3, 7
	v_cndmask_b32_e64 v8, 0, 1, s[4:5]
	s_cselect_b64 s[4:5], -1, 0
	s_and_b64 s[4:5], s[8:9], s[4:5]
	s_cmp_gt_u32 s3, 8
	v_cndmask_b32_e64 v9, 0, 1, s[4:5]
	s_cselect_b64 s[4:5], -1, 0
	s_and_b64 s[4:5], s[36:37], s[4:5]
	s_cmp_gt_u32 s3, 9
	v_cndmask_b32_e64 v10, 0, 1, s[4:5]
	s_cselect_b64 s[4:5], -1, 0
	s_and_b64 s[4:5], s[10:11], s[4:5]
	s_cmp_gt_u32 s3, 10
	v_cndmask_b32_e64 v11, 0, 1, s[4:5]
	s_cselect_b64 s[4:5], -1, 0
	v_add_u32_e32 v2, v3, v2
	s_and_b64 s[4:5], s[38:39], s[4:5]
	v_add_u32_e32 v2, v2, v4
	s_cmp_gt_u32 s3, 11
	v_add_u32_e32 v2, v2, v5
	v_cndmask_b32_e64 v12, 0, 1, s[4:5]
	s_cselect_b64 s[4:5], -1, 0
	v_add_u32_e32 v2, v2, v6
	s_and_b64 s[4:5], s[12:13], s[4:5]
	v_add_u32_e32 v2, v2, v7
	s_cmp_gt_u32 s3, 12
	v_add_u32_e32 v2, v2, v8
	v_cndmask_b32_e64 v13, 0, 1, s[4:5]
	s_cselect_b64 s[4:5], -1, 0
	v_add_u32_e32 v2, v2, v9
	s_and_b64 s[4:5], s[40:41], s[4:5]
	v_add_u32_e32 v2, v2, v10
	s_cmp_gt_u32 s3, 13
	v_add_u32_e32 v2, v2, v11
	v_cndmask_b32_e64 v14, 0, 1, s[4:5]
	s_cselect_b64 s[4:5], -1, 0
	v_add_u32_e32 v2, v2, v12
	s_and_b64 s[4:5], s[14:15], s[4:5]
	v_add_u32_e32 v2, v2, v13
	v_cndmask_b32_e64 v15, 0, 1, s[4:5]
	s_and_b64 s[4:5], s[18:19], s[42:43]
	v_add_u32_e32 v2, v2, v14
	v_cndmask_b32_e64 v16, 0, 1, s[4:5]
	v_add_u32_e32 v2, v2, v15
	v_add_u32_e32 v2, v2, v16
	s_add_i32 s3, 0, 0x21168
	v_cndmask_b32_e64 v2, 0, v2, s[44:45]
	v_mov_b32_e32 v3, s3
	s_and_b64 s[4:5], s[44:45], exec
	v_add_u32_e32 v0, s33, v0
	ds_write_b32 v3, v2
	s_cselect_b32 s3, s60, s85
	v_mov_b32_e32 v2, s2
	s_add_i32 s2, 0, 0x2116c
	v_cndmask_b32_e64 v2, v2, v0, s[44:45]
	v_mov_b32_e32 v3, s2
	s_add_i32 s2, 0, 0x21170
	ds_write_b32 v3, v2
	v_mov_b32_e32 v2, s2
	v_mov_b32_e32 v3, s3
	s_add_i32 s2, 0, 0x21174
	v_cndmask_b32_e64 v1, 1, v1, s[44:45]
	ds_write_b32 v2, v3
	v_mov_b32_e32 v2, s2
	s_add_i32 s2, 0, 0x21178
	ds_write_b32 v2, v1
	v_mov_b32_e32 v1, s2
	v_mov_b32_e32 v2, 0
	s_add_i32 s2, 0, 0x2117c
	v_cmp_eq_u32_e32 vcc, 0, v0
	ds_write_b32 v1, v2
	v_cndmask_b32_e64 v1, 0, 1, s[44:45]
	v_mov_b32_e32 v2, s2
	s_and_b64 s[2:3], vcc, s[44:45]
	ds_write_b32 v2, v1
	s_and_b64 exec, exec, s[2:3]
	s_cbranch_execz .LBB13_23
	v_mov_b32_e32 v0, 0xb000
	v_mov_b32_e32 v1, 0
	global_store_dword v0, v1, s[22:23] offset:512 sc0
	s_nop 1
	v_mov_b32_e32 v0, 0xc000
	global_store_dword v0, v1, s[22:23] offset:512 sc0
	s_nop 1
	v_mov_b32_e32 v0, 0xd000
	global_store_dword v0, v1, s[22:23] offset:512 sc0
	s_nop 1
	v_mov_b32_e32 v0, 0xe000
	global_store_dword v0, v1, s[22:23] offset:512 sc0
	s_nop 1
	v_mov_b32_e32 v0, 0xf000
	global_store_dword v0, v1, s[22:23] offset:512 sc0
	s_nop 1
	v_mov_b32_e32 v0, 0x10000
	global_store_dword v0, v1, s[22:23] offset:512 sc0
	s_nop 1
	v_mov_b32_e32 v0, 0x11000
	global_store_dword v0, v1, s[22:23] offset:512 sc0
	s_nop 1
	v_mov_b32_e32 v0, 0x12000
	global_store_dword v0, v1, s[22:23] offset:512 sc0
	s_nop 1
	v_mov_b32_e32 v0, 0x13000
	global_store_dword v0, v1, s[22:23] offset:512 sc0
	s_waitcnt vmcnt(0)

; __device__ __forceinline__ int lane_id() { int l; asm volatile("v_mbcnt_lo_u32_b32 %0, -1, 0\n\tv_mbcnt_hi_u32_b32 %0, -1, %0" : "=v"(l)); return l; }
; #define LAS __attribute__((address_space(3)))
; __device__ __forceinline__ void xb_add_l2(unsigned* p, unsigned v) { (void)__hip_atomic_fetch_add(p, v, __ATOMIC_RELAXED, __HIP_MEMORY_SCOPE_WORKGROUP); }
; __device__ __forceinline__ unsigned xb_ld_l2(unsigned* p) { unsigned v; const unsigned z = 0u; asm volatile("global_atomic_add %0, %1, %2, off sc0\n\ts_waitcnt vmcnt(0)" : "=v"(v) : "v"(p), "v"(z) : "memory"); return v; }
; __device__ __forceinline__ unsigned xb_xcc_id() { return (unsigned)__builtin_amdgcn_s_getreg((3 << 11) | 20) & 0xFu; }
; #define XB_SPIN(cond, bar) do { unsigned _sp = 0; while (cond) { __builtin_amdgcn_s_sleep(1); \
;     if ((++_sp & 255u) == 0u) { if (xb_ld(&(bar)[XB_TMO])) break; if (_sp > XB_SPIN_CAP) { atomicAdd(&(bar)[XB_TMO], 1u); break; } } } } while (0)
; __device__ __forceinline__ void xcd_local_barrier(unsigned* bar, volatile LAS unsigned* st, int wid0) {
;     asm volatile("s_waitcnt vmcnt(0)" ::: "memory");
;     __syncthreads();
;     if (wid0 == 0 && lane_id() == 0) {
;         unsigned zo = 0; asm volatile("" : "+s"(zo));
;         unsigned* cnt = bar + zo + XB_LCNT2(xb_xcc_id());
;         const unsigned e = st[6] + 1u; st[6] = e; const unsigned target = e * st[4];
;         xb_add_l2(cnt, 1u);
;         XB_SPIN(xb_ld_l2(cnt) < target, bar);
;         __builtin_amdgcn_fence(__ATOMIC_ACQUIRE, "agent");
;         asm volatile("s_waitcnt vmcnt(0)" ::: "memory");
;     }
;     __syncthreads();
; }
.LBB13_968:
	s_cmp_gt_i32 s89, 7
	s_cselect_b64 s[2:3], -1, 0
	s_and_b64 s[0:1], s[0:1], s[2:3]
	s_andn2_b64 vcc, exec, s[0:1]
	s_cbranch_vccnz .LBB13_1048
	s_load_dword s4, s[86:87], 0xb8
	s_load_dwordx2 s[0:1], s[86:87], 0xa8
	s_getreg_b32 s22, hwreg(HW_REG_XCC_ID, 0, 4)
	s_waitcnt lgkmcnt(0)
	s_mulk_i32 s4, 0xd80
	s_ashr_i32 s5, s4, 31
	s_lshl_b64 s[4:5], s[4:5], 2
	s_add_u32 s0, s0, s4
	s_addc_u32 s1, s1, s5
	s_add_u32 s4, s0, 0x4000
	s_addc_u32 s5, s1, 0
	s_add_i32 s0, 0, 0x2117c
	v_mov_b32_e32 v0, s0
	ds_read_b32 v0, v0
	s_waitcnt lgkmcnt(0)
	v_readfirstlane_b32 s0, v0
	s_cmp_eq_u32 s0, 0
	s_cbranch_scc1 .LBB13_984
	s_waitcnt vmcnt(0)
	v_readlane_b32 s0, v238, 10
	v_readlane_b32 s1, v238, 11
	s_and_b64 vcc, exec, s[0:1]
	s_barrier
	s_cbranch_vccnz .LBB13_991
	v_mbcnt_lo_u32_b32 v0, -1, 0
	v_mbcnt_hi_u32_b32 v0, -1, v0
	s_mov_b32 s9, 0
	v_cmp_eq_u32_e32 vcc, 0, v0
	s_and_saveexec_b64 s[0:1], vcc
	s_cbranch_execz .LBB13_990
	s_mov_b32 s8, 0
	s_lshl_b64 s[8:9], s[8:9], 2
	s_add_u32 s8, s4, s8
	s_getreg_b32 s10, hwreg(HW_REG_XCC_ID, 0, 4)
	s_addc_u32 s9, s5, s9
	s_lshl_b32 s10, s10, 8
	s_and_b32 s10, s10, 0xf00
	s_add_u32 s8, s8, s10
	s_addc_u32 s9, s9, 0
	s_add_u32 s8, s8, 0xc200
	s_addc_u32 s9, s9, 0
	s_add_i32 s10, 0, 0x2116c
	v_mov_b32_e32 v1, s10
	ds_read_b32 v0, v1
	s_add_i32 s10, 0, 0x21170
	s_mov_b64 s[6:7], exec
	s_waitcnt vmcnt(0)
	v_mbcnt_lo_u32_b32 v2, s6, 0
	v_mbcnt_hi_u32_b32 v2, s7, v2
	s_waitcnt lgkmcnt(0)
	v_and_b32_e32 v0, 7, v0
	v_lshlrev_b32_e32 v6, 12, v0
	v_mov_b32_e32 v1, s10
	ds_read_b32 v1, v1
	s_mov_b32 s23, 1
	v_cmp_eq_u32_e32 vcc, 0, v2
	s_and_saveexec_b64 s[10:11], vcc
	s_cbranch_execz .LBB13_974
	s_bcnt1_i32_b64 s6, s[6:7]
	v_mov_b32_e32 v2, 0
	v_mov_b32_e32 v3, s6
	global_atomic_add v6, v3, s[8:9]
.LBB13_974:
	s_or_b64 exec, exec, s[10:11]
	s_waitcnt lgkmcnt(0)
	v_lshrrev_b32_e32 v1, 3, v1
	v_mul_u32_u24_e32 v2, 1, v1
	s_mov_b64 s[6:7], 0
	v_mov_b32_e32 v3, 0
	v_mov_b32_e32 v7, 0
	v_mov_b64_e32 v[0:1], s[8:9]
	s_nop 0
	v_lshl_add_u64 v[0:1], v[0:1], 0, v[6:7]
	s_branch .LBB13_977

; __device__ __forceinline__ int lane_id() { int l; asm volatile("v_mbcnt_lo_u32_b32 %0, -1, 0\n\tv_mbcnt_hi_u32_b32 %0, -1, %0" : "=v"(l)); return l; }
; #define LAS __attribute__((address_space(3)))
; __device__ __forceinline__ void xb_add_l2(unsigned* p, unsigned v) { (void)__hip_atomic_fetch_add(p, v, __ATOMIC_RELAXED, __HIP_MEMORY_SCOPE_WORKGROUP); }
; __device__ __forceinline__ unsigned xb_ld_l2(unsigned* p) { unsigned v; const unsigned z = 0u; asm volatile("global_atomic_add %0, %1, %2, off sc0\n\ts_waitcnt vmcnt(0)" : "=v"(v) : "v"(p), "v"(z) : "memory"); return v; }
; __device__ __forceinline__ unsigned xb_xcc_id() { return (unsigned)__builtin_amdgcn_s_getreg((3 << 11) | 20) & 0xFu; }
; #define XB_SPIN(cond, bar) do { unsigned _sp = 0; while (cond) { __builtin_amdgcn_s_sleep(1); \
;     if ((++_sp & 255u) == 0u) { if (xb_ld(&(bar)[XB_TMO])) break; if (_sp > XB_SPIN_CAP) { atomicAdd(&(bar)[XB_TMO], 1u); break; } } } } while (0)
; __device__ __forceinline__ void xcd_local_barrier(unsigned* bar, volatile LAS unsigned* st, int wid0) {
;     asm volatile("s_waitcnt vmcnt(0)" ::: "memory");
;     __syncthreads();
;     if (wid0 == 0 && lane_id() == 0) {
;         unsigned zo = 0; asm volatile("" : "+s"(zo));
;         unsigned* cnt = bar + zo + XB_LCNT2(xb_xcc_id());
;         const unsigned e = st[6] + 1u; st[6] = e; const unsigned target = e * st[4];
;         xb_add_l2(cnt, 1u);
;         XB_SPIN(xb_ld_l2(cnt) < target, bar);
;         __builtin_amdgcn_fence(__ATOMIC_ACQUIRE, "agent");
;         asm volatile("s_waitcnt vmcnt(0)" ::: "memory");
;     }
;     __syncthreads();
; }
.LBB13_1085:
	s_cmp_gt_i32 s89, 8
	s_cselect_b64 s[2:3], -1, 0
	s_and_b64 s[0:1], s[0:1], s[2:3]
	s_andn2_b64 vcc, exec, s[0:1]
	s_cbranch_vccnz .LBB13_1165
	s_load_dword s4, s[86:87], 0xb8
	s_load_dwordx2 s[0:1], s[86:87], 0xa8
	s_getreg_b32 s22, hwreg(HW_REG_XCC_ID, 0, 4)
	s_waitcnt lgkmcnt(0)
	s_mulk_i32 s4, 0xd80
	s_ashr_i32 s5, s4, 31
	s_lshl_b64 s[4:5], s[4:5], 2
	s_add_u32 s0, s0, s4
	s_addc_u32 s1, s1, s5
	s_add_u32 s4, s0, 0x4000
	s_addc_u32 s5, s1, 0
	s_add_i32 s0, 0, 0x2117c
	s_waitcnt vmcnt(0)
	v_mov_b32_e32 v0, s0
	ds_read_b32 v0, v0
	s_waitcnt lgkmcnt(0)
	v_readfirstlane_b32 s0, v0
	s_cmp_eq_u32 s0, 0
	s_cbranch_scc1 .LBB13_1101
	s_waitcnt vmcnt(0)
	v_readlane_b32 s0, v238, 10
	v_readlane_b32 s1, v238, 11
	s_and_b64 vcc, exec, s[0:1]
	s_barrier
	s_cbranch_vccnz .LBB13_1108
	v_mbcnt_lo_u32_b32 v0, -1, 0
	v_mbcnt_hi_u32_b32 v0, -1, v0
	s_mov_b32 s9, 0
	v_cmp_eq_u32_e32 vcc, 0, v0
	s_and_saveexec_b64 s[0:1], vcc
	s_cbranch_execz .LBB13_1107
	s_mov_b32 s8, 0
	s_lshl_b64 s[8:9], s[8:9], 2
	s_add_u32 s8, s4, s8
	s_getreg_b32 s10, hwreg(HW_REG_XCC_ID, 0, 4)
	s_addc_u32 s9, s5, s9
	s_lshl_b32 s10, s10, 8
	s_and_b32 s10, s10, 0xf00
	s_add_u32 s8, s8, s10
	s_addc_u32 s9, s9, 0
	s_add_u32 s8, s8, 0xc200
	s_addc_u32 s9, s9, 0
	s_add_i32 s10, 0, 0x2116c
	v_mov_b32_e32 v1, s10
	ds_read_b32 v0, v1
	s_add_i32 s10, 0, 0x21170
	s_mov_b64 s[6:7], exec
	v_mbcnt_lo_u32_b32 v2, s6, 0
	v_mbcnt_hi_u32_b32 v2, s7, v2
	s_waitcnt lgkmcnt(0)
	v_and_b32_e32 v0, 7, v0
	v_lshlrev_b32_e32 v6, 12, v0
	v_mov_b32_e32 v1, s10
	ds_read_b32 v1, v1
	s_mov_b32 s23, 1
	v_cmp_eq_u32_e32 vcc, 0, v2
	s_and_saveexec_b64 s[10:11], vcc
	s_cbranch_execz .LBB13_1091
	s_bcnt1_i32_b64 s6, s[6:7]
	v_mov_b32_e32 v2, 0
	v_mov_b32_e32 v3, s6
	global_atomic_add v6, v3, s[8:9]
.LBB13_1091:
	s_or_b64 exec, exec, s[10:11]
	s_waitcnt lgkmcnt(0)
	v_lshrrev_b32_e32 v1, 3, v1
	v_mul_u32_u24_e32 v2, 2, v1
	s_mov_b64 s[6:7], 0
	v_mov_b32_e32 v3, 0
	v_mov_b32_e32 v7, 0
	v_mov_b64_e32 v[0:1], s[8:9]
	s_nop 0
	v_lshl_add_u64 v[0:1], v[0:1], 0, v[6:7]
	s_branch .LBB13_1094

; __device__ __forceinline__ int lane_id() { int l; asm volatile("v_mbcnt_lo_u32_b32 %0, -1, 0\n\tv_mbcnt_hi_u32_b32 %0, -1, %0" : "=v"(l)); return l; }
; #define LAS __attribute__((address_space(3)))
; __device__ __forceinline__ void xb_add_l2(unsigned* p, unsigned v) { (void)__hip_atomic_fetch_add(p, v, __ATOMIC_RELAXED, __HIP_MEMORY_SCOPE_WORKGROUP); }
; __device__ __forceinline__ unsigned xb_ld_l2(unsigned* p) { unsigned v; const unsigned z = 0u; asm volatile("global_atomic_add %0, %1, %2, off sc0\n\ts_waitcnt vmcnt(0)" : "=v"(v) : "v"(p), "v"(z) : "memory"); return v; }
; __device__ __forceinline__ unsigned xb_xcc_id() { return (unsigned)__builtin_amdgcn_s_getreg((3 << 11) | 20) & 0xFu; }
; #define XB_SPIN(cond, bar) do { unsigned _sp = 0; while (cond) { __builtin_amdgcn_s_sleep(1); \
;     if ((++_sp & 255u) == 0u) { if (xb_ld(&(bar)[XB_TMO])) break; if (_sp > XB_SPIN_CAP) { atomicAdd(&(bar)[XB_TMO], 1u); break; } } } } while (0)
; __device__ __forceinline__ void xcd_local_barrier(unsigned* bar, volatile LAS unsigned* st, int wid0) {
;     asm volatile("s_waitcnt vmcnt(0)" ::: "memory");
;     __syncthreads();
;     if (wid0 == 0 && lane_id() == 0) {
;         unsigned zo = 0; asm volatile("" : "+s"(zo));
;         unsigned* cnt = bar + zo + XB_LCNT2(xb_xcc_id());
;         const unsigned e = st[6] + 1u; st[6] = e; const unsigned target = e * st[4];
;         xb_add_l2(cnt, 1u);
;         XB_SPIN(xb_ld_l2(cnt) < target, bar);
;         __builtin_amdgcn_fence(__ATOMIC_ACQUIRE, "agent");
;         asm volatile("s_waitcnt vmcnt(0)" ::: "memory");
;     }
;     __syncthreads();
; }
.LBB13_1946:
	s_cmp_gt_i32 s89, 14
	s_cselect_b64 s[2:3], -1, 0
	s_and_b64 s[0:1], s[0:1], s[2:3]
	s_andn2_b64 vcc, exec, s[0:1]
	s_cbranch_vccnz .LBB13_2026
	s_load_dword s4, s[86:87], 0xb8
	s_load_dwordx2 s[0:1], s[86:87], 0xa8
	s_getreg_b32 s22, hwreg(HW_REG_XCC_ID, 0, 4)
	s_waitcnt lgkmcnt(0)
	s_mulk_i32 s4, 0xd80
	s_ashr_i32 s5, s4, 31
	s_lshl_b64 s[4:5], s[4:5], 2
	s_add_u32 s0, s0, s4
	s_addc_u32 s1, s1, s5
	s_add_u32 s4, s0, 0x4000
	s_addc_u32 s5, s1, 0
	s_add_i32 s0, 0, 0x2117c
	v_mov_b32_e32 v0, s0
	ds_read_b32 v0, v0
	s_waitcnt lgkmcnt(0)
	v_readfirstlane_b32 s0, v0
	s_cmp_eq_u32 s0, 0
	s_cbranch_scc1 .LBB13_1962
	s_waitcnt vmcnt(0)
	v_readlane_b32 s0, v238, 10
	v_readlane_b32 s1, v238, 11
	s_and_b64 vcc, exec, s[0:1]
	s_barrier
	s_cbranch_vccnz .LBB13_1969
	v_mbcnt_lo_u32_b32 v0, -1, 0
	v_mbcnt_hi_u32_b32 v0, -1, v0
	s_mov_b32 s9, 0
	v_cmp_eq_u32_e32 vcc, 0, v0
	s_and_saveexec_b64 s[0:1], vcc
	s_cbranch_execz .LBB13_1968
	s_mov_b32 s8, 0
	s_lshl_b64 s[8:9], s[8:9], 2
	s_add_u32 s8, s4, s8
	s_getreg_b32 s10, hwreg(HW_REG_XCC_ID, 0, 4)
	s_addc_u32 s9, s5, s9
	s_lshl_b32 s10, s10, 8
	s_and_b32 s10, s10, 0xf00
	s_add_u32 s8, s8, s10
	s_addc_u32 s9, s9, 0
	s_add_u32 s8, s8, 0xc200
	s_addc_u32 s9, s9, 0
	s_add_i32 s10, 0, 0x2116c
	v_mov_b32_e32 v1, s10
	ds_read_b32 v0, v1
	s_add_i32 s10, 0, 0x21170
	s_mov_b64 s[6:7], exec
	s_waitcnt vmcnt(0)
	v_mbcnt_lo_u32_b32 v2, s6, 0
	v_mbcnt_hi_u32_b32 v2, s7, v2
	s_waitcnt lgkmcnt(0)
	v_and_b32_e32 v0, 7, v0
	v_lshlrev_b32_e32 v6, 12, v0
	v_mov_b32_e32 v1, s10
	ds_read_b32 v1, v1
	s_mov_b32 s23, 1
	v_cmp_eq_u32_e32 vcc, 0, v2
	s_and_saveexec_b64 s[10:11], vcc
	s_cbranch_execz .LBB13_1952
	s_bcnt1_i32_b64 s6, s[6:7]
	v_mov_b32_e32 v2, 0
	v_mov_b32_e32 v3, s6
	global_atomic_add v6, v3, s[8:9]
.LBB13_1952:
	s_or_b64 exec, exec, s[10:11]
	s_waitcnt lgkmcnt(0)
	v_lshrrev_b32_e32 v1, 3, v1
	v_mul_u32_u24_e32 v2, 3, v1
	s_mov_b64 s[6:7], 0
	v_mov_b32_e32 v3, 0
	v_mov_b32_e32 v7, 0
	v_mov_b64_e32 v[0:1], s[8:9]
	s_nop 0
	v_lshl_add_u64 v[0:1], v[0:1], 0, v[6:7]
	s_branch .LBB13_1955

; __device__ __forceinline__ int lane_id() { int l; asm volatile("v_mbcnt_lo_u32_b32 %0, -1, 0\n\tv_mbcnt_hi_u32_b32 %0, -1, %0" : "=v"(l)); return l; }
; #define LAS __attribute__((address_space(3)))
; __device__ __forceinline__ void xb_add_l2(unsigned* p, unsigned v) { (void)__hip_atomic_fetch_add(p, v, __ATOMIC_RELAXED, __HIP_MEMORY_SCOPE_WORKGROUP); }
; __device__ __forceinline__ unsigned xb_ld_l2(unsigned* p) { unsigned v; const unsigned z = 0u; asm volatile("global_atomic_add %0, %1, %2, off sc0\n\ts_waitcnt vmcnt(0)" : "=v"(v) : "v"(p), "v"(z) : "memory"); return v; }
; __device__ __forceinline__ unsigned xb_xcc_id() { return (unsigned)__builtin_amdgcn_s_getreg((3 << 11) | 20) & 0xFu; }
; #define XB_SPIN(cond, bar) do { unsigned _sp = 0; while (cond) { __builtin_amdgcn_s_sleep(1); \
;     if ((++_sp & 255u) == 0u) { if (xb_ld(&(bar)[XB_TMO])) break; if (_sp > XB_SPIN_CAP) { atomicAdd(&(bar)[XB_TMO], 1u); break; } } } } while (0)
; __device__ __forceinline__ void xcd_local_barrier(unsigned* bar, volatile LAS unsigned* st, int wid0) {
;     asm volatile("s_waitcnt vmcnt(0)" ::: "memory");
;     __syncthreads();
;     if (wid0 == 0 && lane_id() == 0) {
;         unsigned zo = 0; asm volatile("" : "+s"(zo));
;         unsigned* cnt = bar + zo + XB_LCNT2(xb_xcc_id());
;         const unsigned e = st[6] + 1u; st[6] = e; const unsigned target = e * st[4];
;         xb_add_l2(cnt, 1u);
;         XB_SPIN(xb_ld_l2(cnt) < target, bar);
;         __builtin_amdgcn_fence(__ATOMIC_ACQUIRE, "agent");
;         asm volatile("s_waitcnt vmcnt(0)" ::: "memory");
;     }
;     __syncthreads();
; }
.LBB13_2063:
	s_cmp_gt_i32 s89, 15
	s_cselect_b64 s[2:3], -1, 0
	s_and_b64 s[0:1], s[0:1], s[2:3]
	s_andn2_b64 vcc, exec, s[0:1]
	s_cbranch_vccnz .LBB13_2143
	s_load_dword s4, s[86:87], 0xb8
	s_load_dwordx2 s[0:1], s[86:87], 0xa8
	s_getreg_b32 s22, hwreg(HW_REG_XCC_ID, 0, 4)
	s_waitcnt lgkmcnt(0)
	s_mulk_i32 s4, 0xd80
	s_ashr_i32 s5, s4, 31
	s_lshl_b64 s[4:5], s[4:5], 2
	s_add_u32 s0, s0, s4
	s_addc_u32 s1, s1, s5
	s_add_u32 s4, s0, 0x4000
	s_addc_u32 s5, s1, 0
	s_add_i32 s0, 0, 0x2117c
	s_waitcnt vmcnt(0)
	v_mov_b32_e32 v0, s0
	ds_read_b32 v0, v0
	s_waitcnt lgkmcnt(0)
	v_readfirstlane_b32 s0, v0
	s_cmp_eq_u32 s0, 0
	s_cbranch_scc1 .LBB13_2079
	s_waitcnt vmcnt(0)
	v_readlane_b32 s0, v238, 10
	v_readlane_b32 s1, v238, 11
	s_and_b64 vcc, exec, s[0:1]
	s_barrier
	s_cbranch_vccnz .LBB13_2086
	v_mbcnt_lo_u32_b32 v0, -1, 0
	v_mbcnt_hi_u32_b32 v0, -1, v0
	s_mov_b32 s9, 0
	v_cmp_eq_u32_e32 vcc, 0, v0
	s_and_saveexec_b64 s[0:1], vcc
	s_cbranch_execz .LBB13_2085
	s_mov_b32 s8, 0
	s_lshl_b64 s[8:9], s[8:9], 2
	s_add_u32 s8, s4, s8
	s_getreg_b32 s10, hwreg(HW_REG_XCC_ID, 0, 4)
	s_addc_u32 s9, s5, s9
	s_lshl_b32 s10, s10, 8
	s_and_b32 s10, s10, 0xf00
	s_add_u32 s8, s8, s10
	s_addc_u32 s9, s9, 0
	s_add_u32 s8, s8, 0xc200
	s_addc_u32 s9, s9, 0
	s_add_i32 s10, 0, 0x2116c
	v_mov_b32_e32 v1, s10
	ds_read_b32 v0, v1
	s_add_i32 s10, 0, 0x21170
	s_mov_b64 s[6:7], exec
	v_mbcnt_lo_u32_b32 v2, s6, 0
	v_mbcnt_hi_u32_b32 v2, s7, v2
	s_waitcnt lgkmcnt(0)
	v_and_b32_e32 v0, 7, v0
	v_lshlrev_b32_e32 v6, 12, v0
	v_mov_b32_e32 v1, s10
	ds_read_b32 v1, v1
	s_mov_b32 s23, 1
	v_cmp_eq_u32_e32 vcc, 0, v2
	s_and_saveexec_b64 s[10:11], vcc
	s_cbranch_execz .LBB13_2069
	s_bcnt1_i32_b64 s6, s[6:7]
	v_mov_b32_e32 v2, 0
	v_mov_b32_e32 v3, s6
	global_atomic_add v6, v3, s[8:9]
.LBB13_2069:
	s_or_b64 exec, exec, s[10:11]
	s_waitcnt lgkmcnt(0)
	v_lshrrev_b32_e32 v1, 3, v1
	v_mul_u32_u24_e32 v2, 4, v1
	s_mov_b64 s[6:7], 0
	v_mov_b32_e32 v3, 0
	v_mov_b32_e32 v7, 0
	v_mov_b64_e32 v[0:1], s[8:9]
	s_nop 0
	v_lshl_add_u64 v[0:1], v[0:1], 0, v[6:7]
	s_branch .LBB13_2072
